# up-proj: first two counted waits after an epilogue relaxed to vmcnt(24) so they do not wait for the epilogue's 16 stores
# speedup vs baseline: 1.0107x; 1.0023x over previous
; #define PG8_STAGE(bufoff, gbase, voff) do { _Pragma("unroll") for (int _i = 0; _i < 2; ++_i) \
;         __builtin_amdgcn_global_load_lds((const unsigned*)((const char*)(gbase) + (voff)[_i]), (PG8_LAS unsigned*)(lds + (bufoff) + ldsw + _i * 8192), 16, 0, 0); } while (0)
; #define PG8_LDA(dst, b, h) do { _Pragma("unroll") for (int m = 0; m < 4; ++m) _Pragma("unroll") for (int k = 0; k < 2; ++k) dst[m][k] = *(const PG8_LAS bf16x8*)(lds + PG8_SA(b, h) + aoff + m * 2048 + k * 1024); } while (0)
; #define PG8_LDB(dst, b, h) do { _Pragma("unroll") for (int n = 0; n < 2; ++n) _Pragma("unroll") for (int k = 0; k < 2; ++k) dst[n][k] = *(const PG8_LAS bf16x8*)(lds + PG8_SB(b, h) + boff + n * 2048 + k * 1024); } while (0)
; #define PG8_WAIT_V(n) asm volatile("s_waitcnt vmcnt(" #n ")" ::: "memory")
; #define PG8_WAIT_L(n) asm volatile("s_waitcnt lgkmcnt(" #n ")" ::: "memory")
; template <class Epi, class Sched, bool ALIGN_EPI = false, bool SP2 = false, class Hook = NoHook, bool REVK = false>
; __device__ __forceinline__ void gemm_phase(PG8_LAS unsigned char* lds, const Gemm g, const Sched& S, const Epi& E, const Hook H = Hook()) {
;     ...
;         const bool has_next = S.next(ui + 1, nxt);
;         const char* nA = has_next ? (const char*)g.A + (size_t)nxt.pm * tstep + krev : cA; const char* nB = has_next ? (const char*)g.Bt + (size_t)nxt.pn * tstep + krev : cB;
;         for (int t = 0; t < nt; t += 2) {
;             if constexpr (Hook::ENABLED) H(acc, t, nt, ui, wr, fr);
;             const bool last = (t == nt - 2);
;             const char* a1 = cA + (long)(t + 1) * kstep;
;             const char* a2 = last ? nA : cA + (long)(t + 2) * kstep; const char* b2 = last ? nB : cB + (long)(t + 2) * kstep;
;             const char* a3 = a2 + kstep; const char* b3 = b2 + kstep;
;             if (last && has_next) S.a_ready(nxt);
;             if constexpr (SP2) {
;             PG8_LDB(B0, 0, 0); PG8_LDB(B1, 0, 1); PG8_SCHED; PG8_LDA(At, 0, 0); PG8_STAGE(PG8_SA(1, 1), a1 + hstep, voffA);
;             PG8_WAIT_V(8); PG8_WAIT_L(0); PG8_BAR; PG8_MMA(0, 0, At, B0); PG8_MMA(0, 1, At, B1); PG8_BAR; PG8_SCHED;
;             PG8_LDA(At, 0, 1); PG8_STAGE(PG8_SB(0, 0), b2, voffB); PG8_STAGE(PG8_SB(0, 1), b2 + hstep, voffB); PG8_STAGE(PG8_SA(0, 0), a2, voffA);
;             PG8_WAIT_V(8); PG8_WAIT_L(0); PG8_BAR; PG8_MMA(1, 0, At, B0); PG8_MMA(1, 1, At, B1); PG8_BAR; PG8_SCHED;
.LBB0_581:
	s_ashr_i32 s87, s86, 31
	s_lshl_b64 s[26:27], s[86:87], 20
	s_add_u32 s88, s11, s26
	s_addc_u32 s89, s24, s27
	s_and_b64 s[26:27], s[6:7], exec
	s_cselect_b32 s41, s89, s23
	s_cselect_b32 s42, s88, s22
	s_ashr_i32 s85, s84, 31
	s_lshl_b64 s[26:27], s[84:85], 20
	s_add_u32 s90, s28, s26
	s_addc_u32 s91, s29, s27
	s_and_b64 s[26:27], s[6:7], exec
	s_cselect_b32 s43, s91, s21
	s_cselect_b32 s44, s90, s20
	s_add_u32 s22, s22, 0x80080
	s_addc_u32 s23, s23, 0
	s_add_u32 s47, s20, 0x100
	s_addc_u32 s51, s21, 0
	s_mov_b32 s53, -2
	s_add_u32 s20, s22, 0xfff80080
	s_addc_u32 s21, s23, -1
	s_add_i32 s46, 0, 0x10000
	s_cmp_eq_u32 s53, 28
	s_cselect_b32 s27, s41, s21
	s_cselect_b32 s26, s42, s20
	v_add_u32_e32 v144, s46, v147
	s_cselect_b32 s21, s43, s51
	s_cselect_b32 s20, s44, s47
	s_add_i32 s58, 0, 0x14000
	ds_read_b128 v[140:143], v144
	ds_read_b128 v[152:155], v144 offset:1024
	ds_read_b128 v[156:159], v144 offset:2048
	ds_read_b128 v[160:163], v144 offset:3072
	v_add_u32_e32 v144, s58, v147
	ds_read_b128 v[164:167], v144
	ds_read_b128 v[182:185], v144 offset:1024
	ds_read_b128 v[186:189], v144 offset:2048
	ds_read_b128 v[190:193], v144 offset:3072
	v_lshl_add_u64 v[144:145], s[22:23], 0, v[136:137]
	s_add_i32 m0, s30, 0xc000
	ds_read_b128 v[194:197], v150
	ds_read_b128 v[200:203], v150 offset:1024
	ds_read_b128 v[204:207], v150 offset:2048
	ds_read_b128 v[210:213], v150 offset:3072
	ds_read_b128 v[226:229], v150 offset:4096
	ds_read_b128 v[230:233], v150 offset:5120
	ds_read_b128 v[234:237], v150 offset:6144
	ds_read_b128 v[238:241], v150 offset:7168
	global_load_lds_dwordx4 v[144:145], off
	v_lshl_add_u64 v[144:145], s[22:23], 0, v[138:139]
	s_add_i32 m0, s30, 0xe000
	s_nop 0
	global_load_lds_dwordx4 v[144:145], off
	s_cmp_lg_u32 s4, 0
	s_cbranch_scc1 .Lvw_up_0
	s_waitcnt vmcnt(8)
.Lvw_up_0:
	s_waitcnt vmcnt(24)
	s_waitcnt lgkmcnt(0)
	s_setprio 1
	s_barrier
	v_mfma_f32_16x16x32_bf16 v[124:127], v[140:143], v[194:197], 0
	v_mfma_f32_16x16x32_bf16 v[124:127], v[152:155], v[200:203], v[124:127]
	v_mfma_f32_16x16x32_bf16 v[120:123], v[160:163], v[200:203], 0
	v_mfma_f32_16x16x32_bf16 v[120:123], v[156:159], v[194:197], v[120:123]
	v_mfma_f32_16x16x32_bf16 v[116:119], v[164:167], v[194:197], 0
	v_mfma_f32_16x16x32_bf16 v[116:119], v[182:185], v[200:203], v[116:119]
	v_mfma_f32_16x16x32_bf16 v[112:115], v[190:193], v[200:203], 0
	v_mfma_f32_16x16x32_bf16 v[112:115], v[186:189], v[194:197], v[112:115]
	v_mfma_f32_16x16x32_bf16 v[96:99], v[186:189], v[204:207], 0
	v_mfma_f32_16x16x32_bf16 v[96:99], v[190:193], v[210:213], v[96:99]
	v_mfma_f32_16x16x32_bf16 v[100:103], v[182:185], v[210:213], 0
	v_mfma_f32_16x16x32_bf16 v[100:103], v[164:167], v[204:207], v[100:103]
	v_mfma_f32_16x16x32_bf16 v[104:107], v[156:159], v[204:207], 0
	v_mfma_f32_16x16x32_bf16 v[104:107], v[160:163], v[210:213], v[104:107]
	v_mfma_f32_16x16x32_bf16 v[108:111], v[152:155], v[210:213], 0
	v_mfma_f32_16x16x32_bf16 v[108:111], v[140:143], v[204:207], v[108:111]
	v_mfma_f32_16x16x32_bf16 v[92:95], v[140:143], v[226:229], 0
	v_mfma_f32_16x16x32_bf16 v[92:95], v[152:155], v[230:233], v[92:95]
	v_mfma_f32_16x16x32_bf16 v[88:91], v[160:163], v[230:233], 0
	v_mfma_f32_16x16x32_bf16 v[88:91], v[156:159], v[226:229], v[88:91]
	v_mfma_f32_16x16x32_bf16 v[84:87], v[164:167], v[226:229], 0
	v_mfma_f32_16x16x32_bf16 v[84:87], v[182:185], v[230:233], v[84:87]
	v_mfma_f32_16x16x32_bf16 v[80:83], v[190:193], v[230:233], 0
	v_mfma_f32_16x16x32_bf16 v[80:83], v[186:189], v[226:229], v[80:83]
	v_mfma_f32_16x16x32_bf16 v[64:67], v[186:189], v[234:237], 0
	v_mfma_f32_16x16x32_bf16 v[64:67], v[190:193], v[238:241], v[64:67]
	v_mfma_f32_16x16x32_bf16 v[68:71], v[182:185], v[238:241], 0
	v_mfma_f32_16x16x32_bf16 v[68:71], v[164:167], v[234:237], v[68:71]
	v_mfma_f32_16x16x32_bf16 v[72:75], v[156:159], v[234:237], 0
	v_mfma_f32_16x16x32_bf16 v[72:75], v[160:163], v[238:241], v[72:75]
	v_mfma_f32_16x16x32_bf16 v[76:79], v[152:155], v[238:241], 0
	v_mfma_f32_16x16x32_bf16 v[76:79], v[140:143], v[234:237], v[76:79]
	s_barrier
	s_setprio 0
	s_add_i32 s46, s46, s10
	v_lshl_add_u64 v[144:145], s[20:21], 0, v[128:129]
	s_mov_b32 m0, s46
	ds_read_b128 v[194:197], v150 offset:16384
	ds_read_b128 v[200:203], v150 offset:17408
	ds_read_b128 v[204:207], v150 offset:18432
	ds_read_b128 v[210:213], v150 offset:19456
	ds_read_b128 v[226:229], v150 offset:20480
	ds_read_b128 v[230:233], v150 offset:21504
	ds_read_b128 v[234:237], v150 offset:22528
	ds_read_b128 v[238:241], v150 offset:23552
	global_load_lds_dwordx4 v[144:145], off
	s_add_i32 m0, s46, 0x2000
	s_add_u32 s56, s20, 0x80000
	v_lshl_add_u64 v[168:169], s[20:21], 0, v[130:131]
	s_addc_u32 s57, s21, 0
	s_add_i32 s46, s58, s10
	global_load_lds_dwordx4 v[168:169], off
	v_lshl_add_u64 v[214:215], s[56:57], 0, v[128:129]
	s_mov_b32 m0, s46
	v_lshl_add_u64 v[242:243], s[26:27], 0, v[132:133]
	global_load_lds_dwordx4 v[214:215], off
	v_lshl_add_u64 v[214:215], s[56:57], 0, v[130:131]
	s_add_i32 m0, s46, 0x2000
	s_nop 0
	global_load_lds_dwordx4 v[214:215], off
	v_lshl_add_u64 v[214:215], s[26:27], 0, v[134:135]
	s_mov_b32 m0, s30
	s_nop 0
	global_load_lds_dwordx4 v[214:215], off
	s_mov_b32 m0, s31
	s_nop 0
	global_load_lds_dwordx4 v[242:243], off
	s_cmp_lg_u32 s4, 0
	s_cbranch_scc1 .Lvw_up_1
	s_waitcnt vmcnt(8)
; #define PG8_STAGE(bufoff, gbase, voff) do { _Pragma("unroll") for (int _i = 0; _i < 2; ++_i) \
;         __builtin_amdgcn_global_load_lds((const unsigned*)((const char*)(gbase) + (voff)[_i]), (PG8_LAS unsigned*)(lds + (bufoff) + ldsw + _i * 8192), 16, 0, 0); } while (0)
; #define PG8_LDA(dst, b, h) do { _Pragma("unroll") for (int m = 0; m < 4; ++m) _Pragma("unroll") for (int k = 0; k < 2; ++k) dst[m][k] = *(const PG8_LAS bf16x8*)(lds + PG8_SA(b, h) + aoff + m * 2048 + k * 1024); } while (0)
; #define PG8_LDB(dst, b, h) do { _Pragma("unroll") for (int n = 0; n < 2; ++n) _Pragma("unroll") for (int k = 0; k < 2; ++k) dst[n][k] = *(const PG8_LAS bf16x8*)(lds + PG8_SB(b, h) + boff + n * 2048 + k * 1024); } while (0)
; #define PG8_MMA(ai, bj, At, Bt) do { __builtin_amdgcn_s_setprio(1); _Pragma("unroll") for (int m = 0; m < 4; ++m) _Pragma("unroll") for (int n = 0; n < 2; ++n) _Pragma("unroll") for (int k = 0; k < 2; ++k) \
;         acc[ai][bj][m][n] = __builtin_amdgcn_mfma_f32_16x16x32_bf16(Bt[n][k], At[m][k], acc[ai][bj][m][n], 0, 0, 0); __builtin_amdgcn_s_setprio(0); } while (0)
; #define PG8_WAIT_V(n) asm volatile("s_waitcnt vmcnt(" #n ")" ::: "memory")
; #define PG8_WAIT_L(n) asm volatile("s_waitcnt lgkmcnt(" #n ")" ::: "memory")
; #define PG8_BAR __builtin_amdgcn_s_barrier()
; #define PG8_SCHED __builtin_amdgcn_sched_barrier(0)
; template <class Epi, class Sched, bool ALIGN_EPI = false, bool SP2 = false, class Hook = NoHook, bool REVK = false>
; __device__ __forceinline__ void gemm_phase(PG8_LAS unsigned char* lds, const Gemm g, const Sched& S, const Epi& E, const Hook H = Hook()) {
;     ...
;             PG8_WAIT_V(8); PG8_WAIT_L(0); PG8_BAR; PG8_MMA(1, 0, At, B0); PG8_MMA(1, 1, At, B1); PG8_BAR; PG8_SCHED;
;             PG8_LDB(B0, 1, 0); PG8_LDB(B1, 1, 1); PG8_SCHED; PG8_LDA(At, 1, 0); PG8_STAGE(PG8_SA(0, 1), a2 + hstep, voffA);
;             PG8_WAIT_V(8); PG8_WAIT_L(0); PG8_BAR; PG8_MMA(0, 0, At, B0); PG8_MMA(0, 1, At, B1); PG8_BAR; PG8_SCHED;
.Lvw_up_1:
	s_waitcnt vmcnt(24)
	s_waitcnt lgkmcnt(0)
	s_setprio 1
	s_barrier
	v_mfma_f32_16x16x32_bf16 v[60:63], v[140:143], v[194:197], 0
	v_mfma_f32_16x16x32_bf16 v[60:63], v[152:155], v[200:203], v[60:63]
	v_mfma_f32_16x16x32_bf16 v[56:59], v[160:163], v[200:203], 0
	v_mfma_f32_16x16x32_bf16 v[56:59], v[156:159], v[194:197], v[56:59]
	v_mfma_f32_16x16x32_bf16 v[52:55], v[164:167], v[194:197], 0
	v_mfma_f32_16x16x32_bf16 v[52:55], v[182:185], v[200:203], v[52:55]
	v_mfma_f32_16x16x32_bf16 v[48:51], v[190:193], v[200:203], 0
	v_mfma_f32_16x16x32_bf16 v[48:51], v[186:189], v[194:197], v[48:51]
	v_mfma_f32_16x16x32_bf16 v[32:35], v[186:189], v[204:207], 0
	v_mfma_f32_16x16x32_bf16 v[32:35], v[190:193], v[210:213], v[32:35]
	v_mfma_f32_16x16x32_bf16 v[36:39], v[182:185], v[210:213], 0
	v_mfma_f32_16x16x32_bf16 v[36:39], v[164:167], v[204:207], v[36:39]
	v_mfma_f32_16x16x32_bf16 v[40:43], v[156:159], v[204:207], 0
	v_mfma_f32_16x16x32_bf16 v[40:43], v[160:163], v[210:213], v[40:43]
	v_mfma_f32_16x16x32_bf16 v[44:47], v[152:155], v[210:213], 0
	v_mfma_f32_16x16x32_bf16 v[44:47], v[140:143], v[204:207], v[44:47]
	v_mfma_f32_16x16x32_bf16 v[28:31], v[140:143], v[226:229], 0
	v_mfma_f32_16x16x32_bf16 v[28:31], v[152:155], v[230:233], v[28:31]
	v_mfma_f32_16x16x32_bf16 v[24:27], v[160:163], v[230:233], 0
	v_mfma_f32_16x16x32_bf16 v[24:27], v[156:159], v[226:229], v[24:27]
	v_mfma_f32_16x16x32_bf16 v[20:23], v[164:167], v[226:229], 0
	v_mfma_f32_16x16x32_bf16 v[20:23], v[182:185], v[230:233], v[20:23]
	v_mfma_f32_16x16x32_bf16 v[16:19], v[190:193], v[230:233], 0
	v_mfma_f32_16x16x32_bf16 v[16:19], v[186:189], v[226:229], v[16:19]
	v_mfma_f32_16x16x32_bf16 v[0:3], v[186:189], v[234:237], 0
	v_mfma_f32_16x16x32_bf16 v[0:3], v[190:193], v[238:241], v[0:3]
	v_mfma_f32_16x16x32_bf16 v[4:7], v[182:185], v[238:241], 0
	v_mfma_f32_16x16x32_bf16 v[4:7], v[164:167], v[234:237], v[4:7]
	v_mfma_f32_16x16x32_bf16 v[8:11], v[156:159], v[234:237], 0
	v_mfma_f32_16x16x32_bf16 v[8:11], v[160:163], v[238:241], v[8:11]
	v_mfma_f32_16x16x32_bf16 v[12:15], v[152:155], v[238:241], 0
	v_mfma_f32_16x16x32_bf16 v[12:15], v[140:143], v[234:237], v[12:15]
	s_barrier
	s_setprio 0
	s_add_i32 s46, 0, 0x18000
	v_add_u32_e32 v151, s46, v147
	s_add_i32 s56, 0, 0x1c000
	ds_read_b128 v[140:143], v151
	ds_read_b128 v[152:155], v151 offset:1024
	ds_read_b128 v[156:159], v151 offset:2048
	ds_read_b128 v[160:163], v151 offset:3072
	v_add_u32_e32 v151, s56, v147
	ds_read_b128 v[164:167], v151
	ds_read_b128 v[182:185], v151 offset:1024
	ds_read_b128 v[186:189], v151 offset:2048
	ds_read_b128 v[190:193], v151 offset:3072
	s_add_u32 s26, s26, 0x80000
	s_addc_u32 s27, s27, 0
	s_mov_b32 m0, s34
	v_lshl_add_u64 v[244:245], s[26:27], 0, v[134:135]
	ds_read_b128 v[194:197], v150 offset:32768
	ds_read_b128 v[200:203], v150 offset:33792
	ds_read_b128 v[204:207], v150 offset:34816
	ds_read_b128 v[210:213], v150 offset:35840
	ds_read_b128 v[226:229], v150 offset:36864
	ds_read_b128 v[230:233], v150 offset:37888
	ds_read_b128 v[234:237], v150 offset:38912
	ds_read_b128 v[238:241], v150 offset:39936
	global_load_lds_dwordx4 v[244:245], off
	v_lshl_add_u64 v[244:245], s[26:27], 0, v[132:133]
	s_mov_b32 m0, s35
	s_nop 0
	global_load_lds_dwordx4 v[244:245], off
	s_waitcnt vmcnt(8)
	s_waitcnt lgkmcnt(0)
	s_setprio 1
	s_barrier
	v_mfma_f32_16x16x32_bf16 v[124:127], v[140:143], v[194:197], v[124:127]
	v_mfma_f32_16x16x32_bf16 v[124:127], v[152:155], v[200:203], v[124:127]
	v_mfma_f32_16x16x32_bf16 v[120:123], v[160:163], v[200:203], v[120:123]
	v_mfma_f32_16x16x32_bf16 v[120:123], v[156:159], v[194:197], v[120:123]
	v_mfma_f32_16x16x32_bf16 v[116:119], v[164:167], v[194:197], v[116:119]
	v_mfma_f32_16x16x32_bf16 v[116:119], v[182:185], v[200:203], v[116:119]
	v_mfma_f32_16x16x32_bf16 v[112:115], v[190:193], v[200:203], v[112:115]
	v_mfma_f32_16x16x32_bf16 v[112:115], v[186:189], v[194:197], v[112:115]
	v_mfma_f32_16x16x32_bf16 v[96:99], v[186:189], v[204:207], v[96:99]
	v_mfma_f32_16x16x32_bf16 v[96:99], v[190:193], v[210:213], v[96:99]
	v_mfma_f32_16x16x32_bf16 v[100:103], v[182:185], v[210:213], v[100:103]
	v_mfma_f32_16x16x32_bf16 v[100:103], v[164:167], v[204:207], v[100:103]
	v_mfma_f32_16x16x32_bf16 v[104:107], v[156:159], v[204:207], v[104:107]
	v_mfma_f32_16x16x32_bf16 v[104:107], v[160:163], v[210:213], v[104:107]
	v_mfma_f32_16x16x32_bf16 v[108:111], v[152:155], v[210:213], v[108:111]
	v_mfma_f32_16x16x32_bf16 v[108:111], v[140:143], v[204:207], v[108:111]
	v_mfma_f32_16x16x32_bf16 v[92:95], v[140:143], v[226:229], v[92:95]
	v_mfma_f32_16x16x32_bf16 v[92:95], v[152:155], v[230:233], v[92:95]
	v_mfma_f32_16x16x32_bf16 v[88:91], v[160:163], v[230:233], v[88:91]
	v_mfma_f32_16x16x32_bf16 v[88:91], v[156:159], v[226:229], v[88:91]
	v_mfma_f32_16x16x32_bf16 v[84:87], v[164:167], v[226:229], v[84:87]
	v_mfma_f32_16x16x32_bf16 v[84:87], v[182:185], v[230:233], v[84:87]
	v_mfma_f32_16x16x32_bf16 v[80:83], v[190:193], v[230:233], v[80:83]
	v_mfma_f32_16x16x32_bf16 v[80:83], v[186:189], v[226:229], v[80:83]
	v_mfma_f32_16x16x32_bf16 v[64:67], v[186:189], v[234:237], v[64:67]
	v_mfma_f32_16x16x32_bf16 v[64:67], v[190:193], v[238:241], v[64:67]
	v_mfma_f32_16x16x32_bf16 v[68:71], v[182:185], v[238:241], v[68:71]
	v_mfma_f32_16x16x32_bf16 v[68:71], v[164:167], v[234:237], v[68:71]
	v_mfma_f32_16x16x32_bf16 v[72:75], v[156:159], v[234:237], v[72:75]
	v_mfma_f32_16x16x32_bf16 v[72:75], v[160:163], v[238:241], v[72:75]
	v_mfma_f32_16x16x32_bf16 v[76:79], v[152:155], v[238:241], v[76:79]
	v_mfma_f32_16x16x32_bf16 v[76:79], v[140:143], v[234:237], v[76:79]
	s_barrier
; #define PG8_STAGE(bufoff, gbase, voff) do { _Pragma("unroll") for (int _i = 0; _i < 2; ++_i) \
;         __builtin_amdgcn_global_load_lds((const unsigned*)((const char*)(gbase) + (voff)[_i]), (PG8_LAS unsigned*)(lds + (bufoff) + ldsw + _i * 8192), 16, 0, 0); } while (0)
; #define PG8_LDA(dst, b, h) do { _Pragma("unroll") for (int m = 0; m < 4; ++m) _Pragma("unroll") for (int k = 0; k < 2; ++k) dst[m][k] = *(const PG8_LAS bf16x8*)(lds + PG8_SA(b, h) + aoff + m * 2048 + k * 1024); } while (0)
; #define PG8_MMA(ai, bj, At, Bt) do { __builtin_amdgcn_s_setprio(1); _Pragma("unroll") for (int m = 0; m < 4; ++m) _Pragma("unroll") for (int n = 0; n < 2; ++n) _Pragma("unroll") for (int k = 0; k < 2; ++k) \
;         acc[ai][bj][m][n] = __builtin_amdgcn_mfma_f32_16x16x32_bf16(Bt[n][k], At[m][k], acc[ai][bj][m][n], 0, 0, 0); __builtin_amdgcn_s_setprio(0); } while (0)
; #define PG8_WAIT_V(n) asm volatile("s_waitcnt vmcnt(" #n ")" ::: "memory")
; #define PG8_WAIT_L(n) asm volatile("s_waitcnt lgkmcnt(" #n ")" ::: "memory")
; #define PG8_BAR __builtin_amdgcn_s_barrier()
; #define PG8_SCHED __builtin_amdgcn_sched_barrier(0)
; template <class Epi, class Sched, bool ALIGN_EPI = false, bool SP2 = false, class Hook = NoHook, bool REVK = false>
; __device__ __forceinline__ void gemm_phase(PG8_LAS unsigned char* lds, const Gemm g, const Sched& S, const Epi& E, const Hook H = Hook()) {
;     ...
;         for (int t = 0; t < nt; t += 2) {
;     ...
;             PG8_LDA(At, 1, 1); PG8_STAGE(PG8_SB(1, 0), b3, voffB); PG8_STAGE(PG8_SB(1, 1), b3 + hstep, voffB); PG8_STAGE(PG8_SA(1, 0), a3, voffA);
;             PG8_WAIT_V(8); PG8_WAIT_L(0); PG8_BAR; PG8_MMA(1, 0, At, B0); PG8_MMA(1, 1, At, B1); PG8_BAR; PG8_SCHED;
	s_setprio 0
	s_add_i32 s26, s46, s10
	v_lshl_add_u64 v[144:145], v[144:145], 0, s[64:65]
	s_mov_b32 m0, s26
	ds_read_b128 v[194:197], v150 offset:49152
	ds_read_b128 v[200:203], v150 offset:50176
	ds_read_b128 v[204:207], v150 offset:51200
	ds_read_b128 v[210:213], v150 offset:52224
	ds_read_b128 v[226:229], v150 offset:53248
	ds_read_b128 v[230:233], v150 offset:54272
	ds_read_b128 v[234:237], v150 offset:55296
	ds_read_b128 v[238:241], v150 offset:56320
	global_load_lds_dwordx4 v[144:145], off
	s_add_i32 m0, s26, 0x2000
	s_add_u32 s20, s20, 0x80080
	v_lshl_add_u64 v[144:145], v[168:169], 0, s[64:65]
	s_addc_u32 s21, s21, 0
	s_add_i32 s26, s56, s10
	global_load_lds_dwordx4 v[144:145], off
	v_lshl_add_u64 v[144:145], s[20:21], 0, v[128:129]
	s_mov_b32 m0, s26
	s_nop 0
	global_load_lds_dwordx4 v[144:145], off
	v_lshl_add_u64 v[144:145], s[20:21], 0, v[130:131]
	s_add_i32 m0, s26, 0x2000
	s_nop 0
	global_load_lds_dwordx4 v[144:145], off
	v_lshl_add_u64 v[144:145], v[214:215], 0, s[64:65]
	s_mov_b32 m0, s36
	s_nop 0
	global_load_lds_dwordx4 v[144:145], off
	v_lshl_add_u64 v[144:145], v[242:243], 0, s[64:65]
	s_mov_b32 m0, s38
	s_nop 0
	global_load_lds_dwordx4 v[144:145], off
	s_waitcnt vmcnt(8)
	s_waitcnt lgkmcnt(0)
	s_setprio 1
	s_barrier
	v_mfma_f32_16x16x32_bf16 v[60:63], v[140:143], v[194:197], v[60:63]
	v_mfma_f32_16x16x32_bf16 v[60:63], v[152:155], v[200:203], v[60:63]
	v_mfma_f32_16x16x32_bf16 v[56:59], v[160:163], v[200:203], v[56:59]
	v_mfma_f32_16x16x32_bf16 v[56:59], v[156:159], v[194:197], v[56:59]
	v_mfma_f32_16x16x32_bf16 v[52:55], v[164:167], v[194:197], v[52:55]
	v_mfma_f32_16x16x32_bf16 v[52:55], v[182:185], v[200:203], v[52:55]
	v_mfma_f32_16x16x32_bf16 v[48:51], v[190:193], v[200:203], v[48:51]
	v_mfma_f32_16x16x32_bf16 v[48:51], v[186:189], v[194:197], v[48:51]
	v_mfma_f32_16x16x32_bf16 v[32:35], v[186:189], v[204:207], v[32:35]
	v_mfma_f32_16x16x32_bf16 v[32:35], v[190:193], v[210:213], v[32:35]
	v_mfma_f32_16x16x32_bf16 v[36:39], v[182:185], v[210:213], v[36:39]
	v_mfma_f32_16x16x32_bf16 v[36:39], v[164:167], v[204:207], v[36:39]
	v_mfma_f32_16x16x32_bf16 v[40:43], v[156:159], v[204:207], v[40:43]
	v_mfma_f32_16x16x32_bf16 v[40:43], v[160:163], v[210:213], v[40:43]
	v_mfma_f32_16x16x32_bf16 v[44:47], v[152:155], v[210:213], v[44:47]
	v_mfma_f32_16x16x32_bf16 v[44:47], v[140:143], v[204:207], v[44:47]
	v_mfma_f32_16x16x32_bf16 v[28:31], v[140:143], v[226:229], v[28:31]
	v_mfma_f32_16x16x32_bf16 v[28:31], v[152:155], v[230:233], v[28:31]
	v_mfma_f32_16x16x32_bf16 v[24:27], v[160:163], v[230:233], v[24:27]
	v_mfma_f32_16x16x32_bf16 v[24:27], v[156:159], v[226:229], v[24:27]
	v_mfma_f32_16x16x32_bf16 v[20:23], v[164:167], v[226:229], v[20:23]
	v_mfma_f32_16x16x32_bf16 v[20:23], v[182:185], v[230:233], v[20:23]
	v_mfma_f32_16x16x32_bf16 v[16:19], v[190:193], v[230:233], v[16:19]
	v_mfma_f32_16x16x32_bf16 v[16:19], v[186:189], v[226:229], v[16:19]
	v_mfma_f32_16x16x32_bf16 v[0:3], v[186:189], v[234:237], v[0:3]
	v_mfma_f32_16x16x32_bf16 v[0:3], v[190:193], v[238:241], v[0:3]
	v_mfma_f32_16x16x32_bf16 v[4:7], v[182:185], v[238:241], v[4:7]
	v_mfma_f32_16x16x32_bf16 v[4:7], v[164:167], v[234:237], v[4:7]
	v_mfma_f32_16x16x32_bf16 v[8:11], v[156:159], v[234:237], v[8:11]
	v_mfma_f32_16x16x32_bf16 v[8:11], v[160:163], v[238:241], v[8:11]
	v_mfma_f32_16x16x32_bf16 v[12:15], v[152:155], v[238:241], v[12:15]
	v_mfma_f32_16x16x32_bf16 v[12:15], v[140:143], v[234:237], v[12:15]
	s_barrier
	s_setprio 0
	s_add_i32 s53, s53, 2
	s_add_u32 s22, s22, 0x100
	s_addc_u32 s23, s23, 0
	s_add_u32 s47, s47, 0x100
	s_addc_u32 s51, s51, 0
	s_cmp_gt_u32 s53, 29
